# attention: the DMA lane-offset reads for the next iteration issued right after the P conversion instead of after the last PV MFMA (their LDS latency no longer sits in front of the iteration barrier)
# speedup vs baseline: 1.0092x; 1.0001x over previous
.LBB0_2759:
	v_exp_f32_e32 v2, v4
	s_add_i32 s8, s22, 0
	s_add_i32 s8, s8, 0x10000
	v_add_f32_e32 v8, v2, v209
	v_cvt_pk_bf16_f32 v149, v192, v2
	s_waitcnt lgkmcnt(0)
	v_add_u32_e32 v2, s8, v252
	ds_read_b64_tr_b16 v[150:151], v2 offset:0
	ds_read_b64_tr_b16 v[152:153], v2 offset:0x1000
	ds_read_b64_tr_b16 v[154:155], v2 offset:0x2000
	ds_read_b64_tr_b16 v[156:157], v2 offset:0x3000
	ds_read_b64_tr_b16 v[158:159], v2 offset:0x4000
	ds_read_b64_tr_b16 v[160:161], v2 offset:0x5000
	ds_read_b64_tr_b16 v[162:163], v2 offset:0x6000
	ds_read_b64_tr_b16 v[164:165], v2 offset:0x7000
	v_add_f32_e32 v7, v7, v8
	v_add_f32_e32 v250, v250, v7
	v_cvt_pk_bf16_f32 v4, v194, v195
	v_cvt_pk_bf16_f32 v5, v196, v197
	v_cvt_pk_bf16_f32 v6, v198, v199
	v_cvt_pk_bf16_f32 v7, v200, v201
	v_cvt_pk_bf16_f32 v8, v202, v203
	v_cvt_pk_bf16_f32 v9, v204, v205
	v_cvt_pk_bf16_f32 v10, v206, v207
	v_cvt_pk_bf16_f32 v11, v208, v209
	v_cvt_pk_bf16_f32 v12, v178, v179
	v_cvt_pk_bf16_f32 v13, v180, v181
	v_cvt_pk_bf16_f32 v14, v182, v183
	v_cvt_pk_bf16_f32 v15, v184, v185
	v_cvt_pk_bf16_f32 v146, v186, v187
	v_cvt_pk_bf16_f32 v147, v188, v189
	v_cvt_pk_bf16_f32 v148, v190, v191
	v_lshl_add_u32 v200, v242, 5, s32
	ds_read_b128 v[204:207], v200 offset:16
	ds_read_b128 v[200:203], v200
	ds_read_b64_tr_b16 v[166:167], v2 offset:0x200
	ds_read_b64_tr_b16 v[168:169], v2 offset:0x1200
	ds_read_b64_tr_b16 v[170:171], v2 offset:0x2200
	ds_read_b64_tr_b16 v[172:173], v2 offset:0x3200
	ds_read_b64_tr_b16 v[174:175], v2 offset:0x4200
	ds_read_b64_tr_b16 v[176:177], v2 offset:0x5200
	ds_read_b64_tr_b16 v[178:179], v2 offset:0x6200
	ds_read_b64_tr_b16 v[180:181], v2 offset:0x7200
	s_waitcnt lgkmcnt(8)
	v_mfma_f32_32x32x16_bf16 v[114:129], v[4:7], v[150:153], v[114:129]
	v_mfma_f32_32x32x16_bf16 v[114:129], v[8:11], v[154:157], v[114:129]
	v_mfma_f32_32x32x16_bf16 v[114:129], v[12:15], v[158:161], v[114:129]
	v_mfma_f32_32x32x16_bf16 v[114:129], v[146:149], v[162:165], v[114:129]
	ds_read_b64_tr_b16 v[150:151], v2 offset:0x400
	ds_read_b64_tr_b16 v[152:153], v2 offset:0x1400
	ds_read_b64_tr_b16 v[154:155], v2 offset:0x2400
	ds_read_b64_tr_b16 v[156:157], v2 offset:0x3400
	ds_read_b64_tr_b16 v[158:159], v2 offset:0x4400
	ds_read_b64_tr_b16 v[160:161], v2 offset:0x5400
	ds_read_b64_tr_b16 v[162:163], v2 offset:0x6400
	ds_read_b64_tr_b16 v[164:165], v2 offset:0x7400
	s_waitcnt lgkmcnt(8)
	v_mfma_f32_32x32x16_bf16 v[98:113], v[4:7], v[166:169], v[98:113]
	v_mfma_f32_32x32x16_bf16 v[98:113], v[8:11], v[170:173], v[98:113]
	v_mfma_f32_32x32x16_bf16 v[98:113], v[12:15], v[174:177], v[98:113]
	v_mfma_f32_32x32x16_bf16 v[98:113], v[146:149], v[178:181], v[98:113]
	ds_read_b64_tr_b16 v[166:167], v2 offset:0x600
	ds_read_b64_tr_b16 v[168:169], v2 offset:0x1600
	ds_read_b64_tr_b16 v[170:171], v2 offset:0x2600
	ds_read_b64_tr_b16 v[172:173], v2 offset:0x3600
	ds_read_b64_tr_b16 v[174:175], v2 offset:0x4600
	ds_read_b64_tr_b16 v[176:177], v2 offset:0x5600
	ds_read_b64_tr_b16 v[178:179], v2 offset:0x6600
	ds_read_b64_tr_b16 v[180:181], v2 offset:0x7600
	s_waitcnt lgkmcnt(8)
	v_mfma_f32_32x32x16_bf16 v[130:145], v[4:7], v[150:153], v[130:145]
	v_mfma_f32_32x32x16_bf16 v[130:145], v[8:11], v[154:157], v[130:145]
	v_mfma_f32_32x32x16_bf16 v[130:145], v[12:15], v[158:161], v[130:145]
	v_mfma_f32_32x32x16_bf16 v[130:145], v[146:149], v[162:165], v[130:145]
	ds_read_b64_tr_b16 v[150:151], v2 offset:0x800
	ds_read_b64_tr_b16 v[152:153], v2 offset:0x1800
	ds_read_b64_tr_b16 v[154:155], v2 offset:0x2800
	ds_read_b64_tr_b16 v[156:157], v2 offset:0x3800
	ds_read_b64_tr_b16 v[158:159], v2 offset:0x4800
	ds_read_b64_tr_b16 v[160:161], v2 offset:0x5800
	ds_read_b64_tr_b16 v[162:163], v2 offset:0x6800
	ds_read_b64_tr_b16 v[164:165], v2 offset:0x7800
	s_waitcnt lgkmcnt(8)
	v_mfma_f32_32x32x16_bf16 v[82:97], v[4:7], v[166:169], v[82:97]
	v_mfma_f32_32x32x16_bf16 v[82:97], v[8:11], v[170:173], v[82:97]
	v_mfma_f32_32x32x16_bf16 v[82:97], v[12:15], v[174:177], v[82:97]
	v_mfma_f32_32x32x16_bf16 v[82:97], v[146:149], v[178:181], v[82:97]
	ds_read_b64_tr_b16 v[166:167], v2 offset:0xa00
	ds_read_b64_tr_b16 v[168:169], v2 offset:0x1a00
	ds_read_b64_tr_b16 v[170:171], v2 offset:0x2a00
	ds_read_b64_tr_b16 v[172:173], v2 offset:0x3a00
	ds_read_b64_tr_b16 v[174:175], v2 offset:0x4a00
	ds_read_b64_tr_b16 v[176:177], v2 offset:0x5a00
	ds_read_b64_tr_b16 v[178:179], v2 offset:0x6a00
	ds_read_b64_tr_b16 v[180:181], v2 offset:0x7a00
	s_waitcnt lgkmcnt(8)
	v_mfma_f32_32x32x16_bf16 v[66:81], v[4:7], v[150:153], v[66:81]
	v_mfma_f32_32x32x16_bf16 v[66:81], v[8:11], v[154:157], v[66:81]
	v_mfma_f32_32x32x16_bf16 v[66:81], v[12:15], v[158:161], v[66:81]
	v_mfma_f32_32x32x16_bf16 v[66:81], v[146:149], v[162:165], v[66:81]
	ds_read_b64_tr_b16 v[150:151], v2 offset:0xc00
	ds_read_b64_tr_b16 v[152:153], v2 offset:0x1c00
	ds_read_b64_tr_b16 v[154:155], v2 offset:0x2c00
	ds_read_b64_tr_b16 v[156:157], v2 offset:0x3c00
	ds_read_b64_tr_b16 v[158:159], v2 offset:0x4c00
	ds_read_b64_tr_b16 v[160:161], v2 offset:0x5c00
	ds_read_b64_tr_b16 v[162:163], v2 offset:0x6c00
	ds_read_b64_tr_b16 v[164:165], v2 offset:0x7c00
	s_waitcnt lgkmcnt(8)
	v_mfma_f32_32x32x16_bf16 v[50:65], v[4:7], v[166:169], v[50:65]
	v_mfma_f32_32x32x16_bf16 v[50:65], v[8:11], v[170:173], v[50:65]
	v_mfma_f32_32x32x16_bf16 v[50:65], v[12:15], v[174:177], v[50:65]
	v_mfma_f32_32x32x16_bf16 v[50:65], v[146:149], v[178:181], v[50:65]
	ds_read_b64_tr_b16 v[166:167], v2 offset:0xe00
	ds_read_b64_tr_b16 v[168:169], v2 offset:0x1e00
	ds_read_b64_tr_b16 v[170:171], v2 offset:0x2e00
	ds_read_b64_tr_b16 v[172:173], v2 offset:0x3e00
	ds_read_b64_tr_b16 v[174:175], v2 offset:0x4e00
	ds_read_b64_tr_b16 v[176:177], v2 offset:0x5e00
	ds_read_b64_tr_b16 v[178:179], v2 offset:0x6e00
	ds_read_b64_tr_b16 v[180:181], v2 offset:0x7e00
	s_waitcnt lgkmcnt(8)
	v_mfma_f32_32x32x16_bf16 v[34:49], v[4:7], v[150:153], v[34:49]
	v_mfma_f32_32x32x16_bf16 v[34:49], v[8:11], v[154:157], v[34:49]
	v_mfma_f32_32x32x16_bf16 v[34:49], v[12:15], v[158:161], v[34:49]
	v_mfma_f32_32x32x16_bf16 v[34:49], v[146:149], v[162:165], v[34:49]
	s_waitcnt lgkmcnt(0)
	v_mfma_f32_32x32x16_bf16 v[18:33], v[4:7], v[166:169], v[18:33]
	v_mfma_f32_32x32x16_bf16 v[18:33], v[8:11], v[170:173], v[18:33]
	v_mfma_f32_32x32x16_bf16 v[18:33], v[12:15], v[174:177], v[18:33]
	v_mfma_f32_32x32x16_bf16 v[18:33], v[146:149], v[178:181], v[18:33]
